# prep tiles: token-shift mix vectors and rw_kk preloaded once per phase into registers (no per-item L2 round trip)
# speedup vs baseline: 1.0003x; 1.0003x over previous
.Lpi0_done_att:
	s_mov_b32 s2, 0x38e38e39
	v_mov_b32_e32 v190, v232
	v_mul_hi_u32 v191, v190, s2
	v_lshrrev_b32_e32 v191, 6, v191
	v_mul_u32_u24_e32 v191, 0x120, v191
	v_sub_u32_e32 v190, v190, v191
	v_lshlrev_b32_e32 v190, 4, v190
	global_load_dwordx4 v[190:193], v190, s[40:41]
	v_add_u32_e32 v194, 0x200, v232
	v_mul_hi_u32 v195, v194, s2
	v_lshrrev_b32_e32 v195, 6, v195
	v_mul_u32_u24_e32 v195, 0x120, v195
	v_sub_u32_e32 v194, v194, v195
	v_lshlrev_b32_e32 v194, 4, v194
	global_load_dwordx4 v[194:197], v194, s[40:41]
	v_add_u32_e32 v198, 0x400, v232
	v_mul_hi_u32 v199, v198, s2
	v_lshrrev_b32_e32 v199, 6, v199
	v_mul_u32_u24_e32 v199, 0x120, v199
	v_sub_u32_e32 v198, v198, v199
	v_lshlrev_b32_e32 v198, 4, v198
	global_load_dwordx4 v[198:201], v198, s[40:41]
	v_add_u32_e32 v202, 0x600, v232
	v_mul_hi_u32 v203, v202, s2
	v_lshrrev_b32_e32 v203, 6, v203
	v_mul_u32_u24_e32 v203, 0x120, v203
	v_sub_u32_e32 v202, v202, v203
	v_lshlrev_b32_e32 v202, 4, v202
	global_load_dwordx4 v[202:205], v202, s[40:41]
	v_add_u32_e32 v206, 0x800, v232
	v_mul_hi_u32 v207, v206, s2
	v_lshrrev_b32_e32 v207, 6, v207
	v_mul_u32_u24_e32 v207, 0x120, v207
	v_sub_u32_e32 v206, v206, v207
	v_lshlrev_b32_e32 v206, 4, v206
	global_load_dwordx4 v[206:209], v206, s[40:41]
	v_add_u32_e32 v210, 0xa00, v232
	v_mul_hi_u32 v211, v210, s2
	v_lshrrev_b32_e32 v211, 6, v211
	v_mul_u32_u24_e32 v211, 0x120, v211
	v_sub_u32_e32 v210, v210, v211
	v_lshlrev_b32_e32 v210, 4, v210
	global_load_dwordx4 v[210:213], v210, s[40:41]
	v_add_u32_e32 v214, 0xc00, v232
	v_mul_hi_u32 v215, v214, s2
	v_lshrrev_b32_e32 v215, 6, v215
	v_mul_u32_u24_e32 v215, 0x120, v215
	v_sub_u32_e32 v214, v214, v215
	v_lshlrev_b32_e32 v214, 4, v214
	global_load_dwordx4 v[214:217], v214, s[40:41]
	v_add_u32_e32 v218, 0xe00, v232
	v_mul_hi_u32 v219, v218, s2
	v_lshrrev_b32_e32 v219, 6, v219
	v_mul_u32_u24_e32 v219, 0x120, v219
	v_sub_u32_e32 v218, v218, v219
	v_lshlrev_b32_e32 v218, 4, v218
	global_load_dwordx4 v[218:221], v218, s[40:41]
	v_add_u32_e32 v222, 0x1000, v232
	v_mul_hi_u32 v223, v222, s2
	v_lshrrev_b32_e32 v223, 6, v223
	v_mul_u32_u24_e32 v223, 0x120, v223
	v_sub_u32_e32 v222, v222, v223
	v_lshlrev_b32_e32 v222, 4, v222
	global_load_dwordx4 v[222:225], v222, s[40:41]
	v_readlane_b32 s2, v250, 60
	v_and_b32_e32 v226, 63, v232
	s_nop 1
	v_or_b32_e32 v226, s2, v226
	v_readlane_b32 s2, v251, 14
	v_readlane_b32 s3, v251, 15
	v_lshlrev_b32_e32 v226, 2, v226
	s_nop 4
	global_load_dword v227, v226, s[2:3] offset:256
	global_load_dword v228, v226, s[2:3] offset:512
	global_load_dword v229, v226, s[2:3] offset:768
	global_load_dword v226, v226, s[2:3]
	s_abs_i32 s37, s80
	v_cvt_f32_u32_e32 v0, s37
	s_ashr_i32 s2, s80, 31
	v_writelane_b32 v249, s2, 36
	s_sub_i32 s2, 0, s37
	v_rcp_iflag_f32_e32 v0, v0
	s_nop 0
	v_mul_f32_e32 v0, 0x4f7ffffe, v0
	v_cvt_u32_f32_e32 v0, v0
	s_nop 0
	v_readfirstlane_b32 s3, v0
	s_mul_i32 s2, s2, s3
	s_mul_hi_u32 s2, s3, s2
	s_add_i32 s2, s3, s2
	v_writelane_b32 v249, s2, 37
	s_branch .LBB0_532

.LBB0_541:
	v_mov_b32_e32 v26, v232
	s_mov_b32 s2, 0x38e38e39
	s_waitcnt vmcnt(8)
	v_lshlrev_b32_e32 v8, 16, v58
	v_mul_hi_i32 v0, v26, s2
	v_lshrrev_b32_e32 v2, 31, v0
	v_ashrrev_i32_e32 v0, 6, v0
	v_add_u32_e32 v29, v0, v2
	s_movk_i32 s2, 0xfee0
	v_mad_i32_i24 v27, v29, s2, v26
	v_lshlrev_b32_e32 v6, 2, v27
	v_ashrrev_i32_e32 v7, 31, v6
	v_lshl_add_u64 v[2:3], v[6:7], 2, s[76:77]
	v_and_b32_e32 v9, 0xffff0000, v58
	v_lshlrev_b32_e32 v10, 16, v59
	v_and_b32_e32 v11, 0xffff0000, v59
	v_lshlrev_b32_e32 v0, 16, v60
	v_and_b32_e32 v12, 0xffff0000, v60
	v_lshlrev_b32_e32 v14, 16, v61
	v_and_b32_e32 v15, 0xffff0000, v61
	v_sub_f32_e32 v13, v12, v9
	v_sub_f32_e32 v12, v0, v8
	v_sub_f32_e32 v15, v15, v11
	v_sub_f32_e32 v14, v14, v10
	v_and_b32_e32 v0, 0xffffffe0, v27
	s_movk_i32 s2, 0xdf
	v_cmp_lt_i32_e32 vcc, s2, v0
	s_waitcnt vmcnt(0)
	v_pk_fma_f32 v[4:5], v[14:15], v[192:193], v[10:11]
	v_pk_fma_f32 v[2:3], v[12:13], v[190:191], v[8:9]
	s_and_saveexec_b64 s[26:27], vcc
	s_xor_b64 s[26:27], exec, s[26:27]
	s_cbranch_execz .LBB0_545
	s_movk_i32 s2, 0xe0
	v_cmp_eq_u32_e32 vcc, s2, v0
	s_and_saveexec_b64 s[42:43], vcc
	s_cbranch_execz .LBB0_544
	v_add_f32_e32 v0, v2, v2
	v_mul_f32_e32 v0, 0x3fb8aa3b, v0
	v_exp_f32_e32 v0, v0
	v_add_f32_e32 v2, v3, v3
	v_mul_f32_e32 v2, 0x3fb8aa3b, v2
	v_exp_f32_e32 v3, v2
	v_add_f32_e32 v0, 1.0, v0
	v_rcp_f32_e32 v2, v0
	v_add_f32_e32 v0, v4, v4
	v_mul_f32_e32 v0, 0x3fb8aa3b, v0
	v_add_f32_e32 v4, v5, v5
	v_exp_f32_e32 v0, v0
	v_mul_f32_e32 v4, 0x3fb8aa3b, v4
	v_exp_f32_e32 v5, v4
	v_add_f32_e32 v3, 1.0, v3
	v_add_f32_e32 v0, 1.0, v0
	v_rcp_f32_e32 v4, v0
	v_add_f32_e32 v0, 1.0, v5
	v_rcp_f32_e32 v5, v0
	v_rcp_f32_e32 v3, v3
	v_pk_fma_f32 v[4:5], v[4:5], -2.0, 1.0 op_sel_hi:[1,0,0]
	v_pk_fma_f32 v[2:3], v[2:3], -2.0, 1.0 op_sel_hi:[1,0,0]

.LBB0_555:
	s_or_b64 exec, exec, s[26:27]
	v_add_u32_e32 v0, 0x200, v26
	s_mov_b32 s2, 0x38e38e39
	v_mul_hi_i32 v2, v0, s2
	v_lshrrev_b32_e32 v3, 31, v2
	v_ashrrev_i32_e32 v2, 6, v2
	v_add_u32_e32 v31, v2, v3
	s_movk_i32 s2, 0xfee0
	v_mad_i32_i24 v28, v31, s2, v0
	v_lshlrev_b32_e32 v8, 2, v28
	v_ashrrev_i32_e32 v9, 31, v8
	v_lshl_add_u64 v[2:3], v[8:9], 2, s[76:77]
	v_lshlrev_b32_e32 v10, 16, v62
	v_and_b32_e32 v11, 0xffff0000, v62
	v_lshlrev_b32_e32 v12, 16, v63
	v_and_b32_e32 v13, 0xffff0000, v63
	v_lshlrev_b32_e32 v0, 16, v64
	v_and_b32_e32 v14, 0xffff0000, v64
	v_lshlrev_b32_e32 v16, 16, v65
	v_and_b32_e32 v17, 0xffff0000, v65
	v_sub_f32_e32 v15, v14, v11
	v_sub_f32_e32 v14, v0, v10
	v_sub_f32_e32 v17, v17, v13
	v_sub_f32_e32 v16, v16, v12
	v_and_b32_e32 v0, 0xffffffe0, v28
	s_movk_i32 s2, 0xdf
	v_cmp_lt_i32_e32 vcc, s2, v0
	v_pk_fma_f32 v[4:5], v[16:17], v[196:197], v[12:13]
	v_pk_fma_f32 v[2:3], v[14:15], v[194:195], v[10:11]
	s_and_saveexec_b64 s[26:27], vcc
	s_xor_b64 s[26:27], exec, s[26:27]
	s_cbranch_execz .LBB0_559
	s_movk_i32 s2, 0xe0
	v_cmp_eq_u32_e32 vcc, s2, v0
	s_and_saveexec_b64 s[42:43], vcc
	s_cbranch_execz .LBB0_558
	v_add_f32_e32 v0, v2, v2
	v_mul_f32_e32 v0, 0x3fb8aa3b, v0
	v_exp_f32_e32 v0, v0
	v_add_f32_e32 v2, v3, v3
	v_mul_f32_e32 v2, 0x3fb8aa3b, v2
	v_exp_f32_e32 v3, v2
	v_add_f32_e32 v0, 1.0, v0
	v_rcp_f32_e32 v2, v0
	v_add_f32_e32 v0, v4, v4
	v_mul_f32_e32 v0, 0x3fb8aa3b, v0
	v_add_f32_e32 v4, v5, v5
	v_exp_f32_e32 v0, v0
	v_mul_f32_e32 v4, 0x3fb8aa3b, v4
	v_exp_f32_e32 v5, v4
	v_add_f32_e32 v3, 1.0, v3
	v_add_f32_e32 v0, 1.0, v0
	v_rcp_f32_e32 v4, v0
	v_add_f32_e32 v0, 1.0, v5
	v_rcp_f32_e32 v5, v0
	v_rcp_f32_e32 v3, v3
	v_pk_fma_f32 v[4:5], v[4:5], -2.0, 1.0 op_sel_hi:[1,0,0]
	v_pk_fma_f32 v[2:3], v[2:3], -2.0, 1.0 op_sel_hi:[1,0,0]

.LBB0_569:
	s_or_b64 exec, exec, s[26:27]
	v_add_u32_e32 v0, 0x400, v26
	s_mov_b32 s2, 0x38e38e39
	v_mul_hi_i32 v2, v0, s2
	v_lshrrev_b32_e32 v3, 31, v2
	v_ashrrev_i32_e32 v2, 6, v2
	v_add_u32_e32 v33, v2, v3
	s_movk_i32 s2, 0xfee0
	v_mad_i32_i24 v30, v33, s2, v0
	v_lshlrev_b32_e32 v10, 2, v30
	v_ashrrev_i32_e32 v11, 31, v10
	v_lshl_add_u64 v[2:3], v[10:11], 2, s[76:77]
	v_lshlrev_b32_e32 v12, 16, v66
	v_and_b32_e32 v13, 0xffff0000, v66
	v_lshlrev_b32_e32 v14, 16, v67
	v_and_b32_e32 v15, 0xffff0000, v67
	v_lshlrev_b32_e32 v0, 16, v68
	v_and_b32_e32 v16, 0xffff0000, v68
	v_lshlrev_b32_e32 v18, 16, v69
	v_and_b32_e32 v19, 0xffff0000, v69
	v_sub_f32_e32 v17, v16, v13
	v_sub_f32_e32 v16, v0, v12
	v_sub_f32_e32 v19, v19, v15
	v_sub_f32_e32 v18, v18, v14
	v_and_b32_e32 v0, 0xffffffe0, v30
	s_movk_i32 s2, 0xdf
	v_cmp_lt_i32_e32 vcc, s2, v0
	v_pk_fma_f32 v[4:5], v[18:19], v[200:201], v[14:15]
	v_pk_fma_f32 v[2:3], v[16:17], v[198:199], v[12:13]
	s_and_saveexec_b64 s[26:27], vcc
	s_xor_b64 s[26:27], exec, s[26:27]
	s_cbranch_execz .LBB0_573
	s_movk_i32 s2, 0xe0
	v_cmp_eq_u32_e32 vcc, s2, v0
	s_and_saveexec_b64 s[42:43], vcc
	s_cbranch_execz .LBB0_572
	v_add_f32_e32 v0, v2, v2
	v_mul_f32_e32 v0, 0x3fb8aa3b, v0
	v_exp_f32_e32 v0, v0
	v_add_f32_e32 v2, v3, v3
	v_mul_f32_e32 v2, 0x3fb8aa3b, v2
	v_exp_f32_e32 v3, v2
	v_add_f32_e32 v0, 1.0, v0
	v_rcp_f32_e32 v2, v0
	v_add_f32_e32 v0, v4, v4
	v_mul_f32_e32 v0, 0x3fb8aa3b, v0
	v_add_f32_e32 v4, v5, v5
	v_exp_f32_e32 v0, v0
	v_mul_f32_e32 v4, 0x3fb8aa3b, v4
	v_exp_f32_e32 v5, v4
	v_add_f32_e32 v3, 1.0, v3
	v_add_f32_e32 v0, 1.0, v0
	v_rcp_f32_e32 v4, v0
	v_add_f32_e32 v0, 1.0, v5
	v_rcp_f32_e32 v5, v0
	v_rcp_f32_e32 v3, v3
	v_pk_fma_f32 v[4:5], v[4:5], -2.0, 1.0 op_sel_hi:[1,0,0]
	v_pk_fma_f32 v[2:3], v[2:3], -2.0, 1.0 op_sel_hi:[1,0,0]

.LBB0_583:
	s_or_b64 exec, exec, s[26:27]
	v_add_u32_e32 v0, 0x600, v26
	s_mov_b32 s2, 0x38e38e39
	v_mul_hi_i32 v2, v0, s2
	v_lshrrev_b32_e32 v3, 31, v2
	v_ashrrev_i32_e32 v2, 6, v2
	v_add_u32_e32 v35, v2, v3
	s_movk_i32 s2, 0xfee0
	v_mad_i32_i24 v32, v35, s2, v0
	v_lshlrev_b32_e32 v12, 2, v32
	v_ashrrev_i32_e32 v13, 31, v12
	v_lshl_add_u64 v[2:3], v[12:13], 2, s[76:77]
	v_lshlrev_b32_e32 v14, 16, v70
	v_and_b32_e32 v15, 0xffff0000, v70
	v_lshlrev_b32_e32 v16, 16, v71
	v_and_b32_e32 v17, 0xffff0000, v71
	v_lshlrev_b32_e32 v0, 16, v72
	v_and_b32_e32 v18, 0xffff0000, v72
	v_lshlrev_b32_e32 v20, 16, v73
	v_and_b32_e32 v21, 0xffff0000, v73
	v_sub_f32_e32 v19, v18, v15
	v_sub_f32_e32 v18, v0, v14
	v_sub_f32_e32 v21, v21, v17
	v_sub_f32_e32 v20, v20, v16
	v_and_b32_e32 v0, 0xffffffe0, v32
	s_movk_i32 s2, 0xdf
	v_cmp_lt_i32_e32 vcc, s2, v0
	v_pk_fma_f32 v[4:5], v[20:21], v[204:205], v[16:17]
	v_pk_fma_f32 v[2:3], v[18:19], v[202:203], v[14:15]
	s_and_saveexec_b64 s[26:27], vcc
	s_xor_b64 s[26:27], exec, s[26:27]
	s_cbranch_execz .LBB0_587
	s_movk_i32 s2, 0xe0
	v_cmp_eq_u32_e32 vcc, s2, v0
	s_and_saveexec_b64 s[42:43], vcc
	s_cbranch_execz .LBB0_586
	v_add_f32_e32 v0, v2, v2
	v_mul_f32_e32 v0, 0x3fb8aa3b, v0
	v_exp_f32_e32 v0, v0
	v_add_f32_e32 v2, v3, v3
	v_mul_f32_e32 v2, 0x3fb8aa3b, v2
	v_exp_f32_e32 v3, v2
	v_add_f32_e32 v0, 1.0, v0
	v_rcp_f32_e32 v2, v0
	v_add_f32_e32 v0, v4, v4
	v_mul_f32_e32 v0, 0x3fb8aa3b, v0
	v_add_f32_e32 v4, v5, v5
	v_exp_f32_e32 v0, v0
	v_mul_f32_e32 v4, 0x3fb8aa3b, v4
	v_exp_f32_e32 v5, v4
	v_add_f32_e32 v3, 1.0, v3
	v_add_f32_e32 v0, 1.0, v0
	v_rcp_f32_e32 v4, v0
	v_add_f32_e32 v0, 1.0, v5
	v_rcp_f32_e32 v5, v0
	v_rcp_f32_e32 v3, v3
	v_pk_fma_f32 v[4:5], v[4:5], -2.0, 1.0 op_sel_hi:[1,0,0]
	v_pk_fma_f32 v[2:3], v[2:3], -2.0, 1.0 op_sel_hi:[1,0,0]

.LBB0_597:
	s_or_b64 exec, exec, s[26:27]
	v_add_u32_e32 v0, 0x800, v26
	s_mov_b32 s2, 0x38e38e39
	v_mul_hi_i32 v2, v0, s2
	v_lshrrev_b32_e32 v3, 31, v2
	v_ashrrev_i32_e32 v2, 6, v2
	v_add_u32_e32 v37, v2, v3
	s_movk_i32 s2, 0xfee0
	v_mad_i32_i24 v34, v37, s2, v0
	v_lshlrev_b32_e32 v14, 2, v34
	v_ashrrev_i32_e32 v15, 31, v14
	v_lshl_add_u64 v[2:3], v[14:15], 2, s[76:77]
	v_lshlrev_b32_e32 v16, 16, v74
	v_and_b32_e32 v17, 0xffff0000, v74
	v_lshlrev_b32_e32 v18, 16, v75
	v_and_b32_e32 v19, 0xffff0000, v75
	v_lshlrev_b32_e32 v0, 16, v76
	v_and_b32_e32 v20, 0xffff0000, v76
	v_lshlrev_b32_e32 v22, 16, v77
	v_and_b32_e32 v23, 0xffff0000, v77
	v_sub_f32_e32 v21, v20, v17
	v_sub_f32_e32 v20, v0, v16
	v_sub_f32_e32 v23, v23, v19
	v_sub_f32_e32 v22, v22, v18
	v_and_b32_e32 v0, 0xffffffe0, v34
	s_movk_i32 s2, 0xdf
	v_cmp_lt_i32_e32 vcc, s2, v0
	v_pk_fma_f32 v[4:5], v[22:23], v[208:209], v[18:19]
	v_pk_fma_f32 v[2:3], v[20:21], v[206:207], v[16:17]
	s_and_saveexec_b64 s[26:27], vcc
	s_xor_b64 s[26:27], exec, s[26:27]
	s_cbranch_execz .LBB0_601
	s_movk_i32 s2, 0xe0
	v_cmp_eq_u32_e32 vcc, s2, v0
	s_and_saveexec_b64 s[42:43], vcc
	s_cbranch_execz .LBB0_600
	v_add_f32_e32 v0, v2, v2
	v_mul_f32_e32 v0, 0x3fb8aa3b, v0
	v_exp_f32_e32 v0, v0
	v_add_f32_e32 v2, v3, v3
	v_mul_f32_e32 v2, 0x3fb8aa3b, v2
	v_exp_f32_e32 v3, v2
	v_add_f32_e32 v0, 1.0, v0
	v_rcp_f32_e32 v2, v0
	v_add_f32_e32 v0, v4, v4
	v_mul_f32_e32 v0, 0x3fb8aa3b, v0
	v_add_f32_e32 v4, v5, v5
	v_exp_f32_e32 v0, v0
	v_mul_f32_e32 v4, 0x3fb8aa3b, v4
	v_exp_f32_e32 v5, v4
	v_add_f32_e32 v3, 1.0, v3
	v_add_f32_e32 v0, 1.0, v0
	v_rcp_f32_e32 v4, v0
	v_add_f32_e32 v0, 1.0, v5
	v_rcp_f32_e32 v5, v0
	v_rcp_f32_e32 v3, v3
	v_pk_fma_f32 v[4:5], v[4:5], -2.0, 1.0 op_sel_hi:[1,0,0]
	v_pk_fma_f32 v[2:3], v[2:3], -2.0, 1.0 op_sel_hi:[1,0,0]

.LBB0_611:
	s_or_b64 exec, exec, s[26:27]
	v_add_u32_e32 v0, 0xa00, v26
	s_mov_b32 s2, 0x38e38e39
	v_mul_hi_i32 v2, v0, s2
	v_lshrrev_b32_e32 v3, 31, v2
	v_ashrrev_i32_e32 v2, 6, v2
	v_add_u32_e32 v39, v2, v3
	s_movk_i32 s2, 0xfee0
	v_mad_i32_i24 v36, v39, s2, v0
	v_lshlrev_b32_e32 v16, 2, v36
	v_ashrrev_i32_e32 v17, 31, v16
	v_lshl_add_u64 v[2:3], v[16:17], 2, s[76:77]
	v_lshlrev_b32_e32 v18, 16, v78
	v_and_b32_e32 v19, 0xffff0000, v78
	v_lshlrev_b32_e32 v20, 16, v79
	v_and_b32_e32 v21, 0xffff0000, v79
	v_lshlrev_b32_e32 v0, 16, v80
	v_and_b32_e32 v22, 0xffff0000, v80
	v_lshlrev_b32_e32 v24, 16, v81
	v_and_b32_e32 v25, 0xffff0000, v81
	v_sub_f32_e32 v23, v22, v19
	v_sub_f32_e32 v22, v0, v18
	v_sub_f32_e32 v25, v25, v21
	v_sub_f32_e32 v24, v24, v20
	v_and_b32_e32 v0, 0xffffffe0, v36
	s_movk_i32 s2, 0xdf
	v_cmp_lt_i32_e32 vcc, s2, v0
	v_pk_fma_f32 v[4:5], v[24:25], v[212:213], v[20:21]
	v_pk_fma_f32 v[2:3], v[22:23], v[210:211], v[18:19]
	s_and_saveexec_b64 s[26:27], vcc
	s_xor_b64 s[26:27], exec, s[26:27]
	s_cbranch_execz .LBB0_615
	s_movk_i32 s2, 0xe0
	v_cmp_eq_u32_e32 vcc, s2, v0
	s_and_saveexec_b64 s[42:43], vcc
	s_cbranch_execz .LBB0_614
	v_add_f32_e32 v0, v2, v2
	v_mul_f32_e32 v0, 0x3fb8aa3b, v0
	v_exp_f32_e32 v0, v0
	v_add_f32_e32 v2, v3, v3
	v_mul_f32_e32 v2, 0x3fb8aa3b, v2
	v_exp_f32_e32 v3, v2
	v_add_f32_e32 v0, 1.0, v0
	v_rcp_f32_e32 v2, v0
	v_add_f32_e32 v0, v4, v4
	v_mul_f32_e32 v0, 0x3fb8aa3b, v0
	v_add_f32_e32 v4, v5, v5
	v_exp_f32_e32 v0, v0
	v_mul_f32_e32 v4, 0x3fb8aa3b, v4
	v_exp_f32_e32 v5, v4
	v_add_f32_e32 v3, 1.0, v3
	v_add_f32_e32 v0, 1.0, v0
	v_rcp_f32_e32 v4, v0
	v_add_f32_e32 v0, 1.0, v5
	v_rcp_f32_e32 v5, v0
	v_rcp_f32_e32 v3, v3
	v_pk_fma_f32 v[4:5], v[4:5], -2.0, 1.0 op_sel_hi:[1,0,0]
	v_pk_fma_f32 v[2:3], v[2:3], -2.0, 1.0 op_sel_hi:[1,0,0]

.LBB0_625:
	s_or_b64 exec, exec, s[26:27]
	v_add_u32_e32 v0, 0xc00, v26
	s_mov_b32 s2, 0x38e38e39
	v_mul_hi_i32 v2, v0, s2
	v_lshrrev_b32_e32 v3, 31, v2
	v_ashrrev_i32_e32 v2, 6, v2
	v_add_u32_e32 v41, v2, v3
	s_movk_i32 s2, 0xfee0
	v_mad_i32_i24 v38, v41, s2, v0
	v_lshlrev_b32_e32 v18, 2, v38
	v_ashrrev_i32_e32 v19, 31, v18
	v_lshl_add_u64 v[2:3], v[18:19], 2, s[76:77]
	v_lshlrev_b32_e32 v20, 16, v82
	v_and_b32_e32 v21, 0xffff0000, v82
	v_lshlrev_b32_e32 v22, 16, v83
	v_and_b32_e32 v23, 0xffff0000, v83
	v_lshlrev_b32_e32 v0, 16, v84
	v_and_b32_e32 v24, 0xffff0000, v84
	v_lshlrev_b32_e32 v40, 16, v85
	v_and_b32_e32 v42, 0xffff0000, v85
	v_sub_f32_e32 v25, v24, v21
	v_sub_f32_e32 v24, v0, v20
	v_sub_f32_e32 v43, v42, v23
	v_sub_f32_e32 v42, v40, v22
	v_and_b32_e32 v0, 0xffffffe0, v38
	s_movk_i32 s2, 0xdf
	v_cmp_lt_i32_e32 vcc, s2, v0
	v_pk_fma_f32 v[4:5], v[42:43], v[216:217], v[22:23]
	v_pk_fma_f32 v[2:3], v[24:25], v[214:215], v[20:21]
	s_and_saveexec_b64 s[26:27], vcc
	s_xor_b64 s[26:27], exec, s[26:27]
	s_cbranch_execz .LBB0_629
	s_movk_i32 s2, 0xe0
	v_cmp_eq_u32_e32 vcc, s2, v0
	s_and_saveexec_b64 s[42:43], vcc
	s_cbranch_execz .LBB0_628
	v_add_f32_e32 v0, v2, v2
	v_mul_f32_e32 v0, 0x3fb8aa3b, v0
	v_exp_f32_e32 v0, v0
	v_add_f32_e32 v2, v3, v3
	v_mul_f32_e32 v2, 0x3fb8aa3b, v2
	v_exp_f32_e32 v3, v2
	v_add_f32_e32 v0, 1.0, v0
	v_rcp_f32_e32 v2, v0
	v_add_f32_e32 v0, v4, v4
	v_mul_f32_e32 v0, 0x3fb8aa3b, v0
	v_add_f32_e32 v4, v5, v5
	v_exp_f32_e32 v0, v0
	v_mul_f32_e32 v4, 0x3fb8aa3b, v4
	v_exp_f32_e32 v5, v4
	v_add_f32_e32 v3, 1.0, v3
	v_add_f32_e32 v0, 1.0, v0
	v_rcp_f32_e32 v4, v0
	v_add_f32_e32 v0, 1.0, v5
	v_rcp_f32_e32 v5, v0
	v_rcp_f32_e32 v3, v3
	v_pk_fma_f32 v[4:5], v[4:5], -2.0, 1.0 op_sel_hi:[1,0,0]
	v_pk_fma_f32 v[2:3], v[2:3], -2.0, 1.0 op_sel_hi:[1,0,0]

.LBB0_639:
	s_or_b64 exec, exec, s[26:27]
	v_add_u32_e32 v0, 0xe00, v26
	s_mov_b32 s2, 0x38e38e39
	v_mul_hi_i32 v2, v0, s2
	v_lshrrev_b32_e32 v3, 31, v2
	v_ashrrev_i32_e32 v2, 6, v2
	v_add_u32_e32 v43, v2, v3
	s_movk_i32 s2, 0xfee0
	v_mad_i32_i24 v40, v43, s2, v0
	v_lshlrev_b32_e32 v20, 2, v40
	v_ashrrev_i32_e32 v21, 31, v20
	v_lshl_add_u64 v[2:3], v[20:21], 2, s[76:77]
	v_lshlrev_b32_e32 v22, 16, v86
	v_and_b32_e32 v23, 0xffff0000, v86
	v_lshlrev_b32_e32 v24, 16, v87
	v_and_b32_e32 v25, 0xffff0000, v87
	v_lshlrev_b32_e32 v0, 16, v88
	v_and_b32_e32 v42, 0xffff0000, v88
	v_lshlrev_b32_e32 v46, 16, v89
	v_and_b32_e32 v47, 0xffff0000, v89
	v_sub_f32_e32 v45, v42, v23
	v_sub_f32_e32 v44, v0, v22
	v_sub_f32_e32 v47, v47, v25
	v_sub_f32_e32 v46, v46, v24
	v_and_b32_e32 v0, 0xffffffe0, v40
	s_movk_i32 s2, 0xdf
	v_cmp_lt_i32_e32 vcc, s2, v0
	v_pk_fma_f32 v[4:5], v[46:47], v[220:221], v[24:25]
	v_pk_fma_f32 v[2:3], v[44:45], v[218:219], v[22:23]
	s_and_saveexec_b64 s[26:27], vcc
	s_xor_b64 s[26:27], exec, s[26:27]
	s_cbranch_execz .LBB0_643
	s_movk_i32 s2, 0xe0
	v_cmp_eq_u32_e32 vcc, s2, v0
	s_and_saveexec_b64 s[42:43], vcc
	s_cbranch_execz .LBB0_642
	v_add_f32_e32 v0, v2, v2
	v_mul_f32_e32 v0, 0x3fb8aa3b, v0
	v_exp_f32_e32 v0, v0
	v_add_f32_e32 v2, v3, v3
	v_mul_f32_e32 v2, 0x3fb8aa3b, v2
	v_exp_f32_e32 v3, v2
	v_add_f32_e32 v0, 1.0, v0
	v_rcp_f32_e32 v2, v0
	v_add_f32_e32 v0, v4, v4
	v_mul_f32_e32 v0, 0x3fb8aa3b, v0
	v_add_f32_e32 v4, v5, v5
	v_exp_f32_e32 v0, v0
	v_mul_f32_e32 v4, 0x3fb8aa3b, v4
	v_exp_f32_e32 v5, v4
	v_add_f32_e32 v3, 1.0, v3
	v_add_f32_e32 v0, 1.0, v0
	v_rcp_f32_e32 v4, v0
	v_add_f32_e32 v0, 1.0, v5
	v_rcp_f32_e32 v5, v0
	v_rcp_f32_e32 v3, v3
	v_pk_fma_f32 v[4:5], v[4:5], -2.0, 1.0 op_sel_hi:[1,0,0]
	v_pk_fma_f32 v[2:3], v[2:3], -2.0, 1.0 op_sel_hi:[1,0,0]

.LBB0_653:
	s_or_b64 exec, exec, s[26:27]
	v_add_u32_e32 v0, 0x1000, v26
	s_mov_b32 s2, 0x38e38e39
	v_mul_hi_i32 v2, v0, s2
	v_lshrrev_b32_e32 v3, 31, v2
	v_ashrrev_i32_e32 v2, 6, v2
	v_add_u32_e32 v45, v2, v3
	s_movk_i32 s2, 0xfee0
	v_mad_i32_i24 v42, v45, s2, v0
	v_lshlrev_b32_e32 v22, 2, v42
	v_ashrrev_i32_e32 v23, 31, v22
	v_lshl_add_u64 v[2:3], v[22:23], 2, s[76:77]
	v_lshlrev_b32_e32 v24, 16, v90
	v_and_b32_e32 v25, 0xffff0000, v90
	v_lshlrev_b32_e32 v46, 16, v91
	v_and_b32_e32 v47, 0xffff0000, v91
	v_lshlrev_b32_e32 v0, 16, v92
	v_and_b32_e32 v44, 0xffff0000, v92
	v_lshlrev_b32_e32 v50, 16, v93
	v_and_b32_e32 v51, 0xffff0000, v93
	v_sub_f32_e32 v49, v44, v25
	v_sub_f32_e32 v48, v0, v24
	v_sub_f32_e32 v51, v51, v47
	v_sub_f32_e32 v50, v50, v46
	v_and_b32_e32 v0, 0xffffffe0, v42
	s_movk_i32 s2, 0xdf
	v_cmp_lt_i32_e32 vcc, s2, v0
	v_pk_fma_f32 v[4:5], v[50:51], v[224:225], v[46:47]
	v_pk_fma_f32 v[2:3], v[48:49], v[222:223], v[24:25]
	s_and_saveexec_b64 s[26:27], vcc
	s_xor_b64 s[26:27], exec, s[26:27]
	s_cbranch_execz .LBB0_657
	s_movk_i32 s2, 0xe0
	v_cmp_eq_u32_e32 vcc, s2, v0
	s_and_saveexec_b64 s[42:43], vcc
	s_cbranch_execz .LBB0_656
	v_add_f32_e32 v0, v2, v2
	v_mul_f32_e32 v0, 0x3fb8aa3b, v0
	v_exp_f32_e32 v0, v0
	v_add_f32_e32 v2, v3, v3
	v_mul_f32_e32 v2, 0x3fb8aa3b, v2
	v_exp_f32_e32 v3, v2
	v_add_f32_e32 v0, 1.0, v0
	v_rcp_f32_e32 v2, v0
	v_add_f32_e32 v0, v4, v4
	v_mul_f32_e32 v0, 0x3fb8aa3b, v0
	v_add_f32_e32 v4, v5, v5
	v_exp_f32_e32 v0, v0
	v_mul_f32_e32 v4, 0x3fb8aa3b, v4
	v_exp_f32_e32 v5, v4
	v_add_f32_e32 v3, 1.0, v3
	v_add_f32_e32 v0, 1.0, v0
	v_rcp_f32_e32 v4, v0
	v_add_f32_e32 v0, 1.0, v5
	v_rcp_f32_e32 v5, v0
	v_rcp_f32_e32 v3, v3
	v_pk_fma_f32 v[4:5], v[4:5], -2.0, 1.0 op_sel_hi:[1,0,0]
	v_pk_fma_f32 v[2:3], v[2:3], -2.0, 1.0 op_sel_hi:[1,0,0]

.LBB0_667:
	s_or_b64 exec, exec, s[26:27]
	v_and_b32_e32 v44, 63, v26
	v_readlane_b32 s2, v250, 60
	v_readlane_b32 s4, v251, 8
	v_readlane_b32 s10, v251, 14
	v_or_b32_e32 v2, s2, v44
	v_ashrrev_i32_e32 v3, 31, v2
	v_readlane_b32 s11, v251, 15
	s_waitcnt lgkmcnt(0)
	s_barrier
	v_lshl_add_u64 v[2:3], v[2:3], 2, s[10:11]
	v_mov_b32_e32 v47, v226
	v_ashrrev_i32_e32 v46, 5, v26
	v_and_b32_e32 v94, -2, v46
	s_movk_i32 s2, 0x1200
	v_lshlrev_b32_e32 v0, 2, v44
	v_mul_lo_u32 v4, v94, s2
	v_add3_u32 v48, 0, v4, v0
	ds_read_b32 v49, v48 offset:1536
	v_readlane_b32 s3, v250, 61
	v_readlane_b32 s2, v252, 20
	v_readlane_b32 s3, v252, 21
	s_ashr_i32 s35, s34, 31
	s_lshl_b64 s[34:35], s[34:35], 4
	v_lshl_add_u64 v[4:5], s[2:3], 0, v[0:1]
	v_ashrrev_i32_e32 v95, 31, v94
	v_lshl_add_u64 v[24:25], s[34:35], 0, v[94:95]
	v_lshlrev_b64 v[24:25], 10, v[24:25]
	v_cmp_eq_u32_e32 vcc, 0, v44
	v_lshl_add_u64 v[24:25], v[4:5], 0, v[24:25]
	v_readlane_b32 s5, v251, 9
	v_readlane_b32 s6, v251, 10
	v_readlane_b32 s7, v251, 11
	v_readlane_b32 s8, v251, 12
	v_readlane_b32 s9, v251, 13
	v_readlane_b32 s12, v251, 16
	v_readlane_b32 s13, v251, 17
	v_readlane_b32 s14, v251, 18
	v_readlane_b32 s15, v251, 19
	v_readlane_b32 s16, v251, 20
	v_readlane_b32 s17, v251, 21
	v_readlane_b32 s18, v251, 22
	v_readlane_b32 s19, v251, 23
	s_waitcnt lgkmcnt(0)
	v_mul_f32_e32 v52, v49, v47
	v_mul_f32_e32 v47, v52, v52
	s_nop 1
	v_mov_b32_dpp v47, v47 quad_perm:[1,0,3,2] row_mask:0xf bank_mask:0xf bound_ctrl:1
	v_fmac_f32_e32 v47, v52, v52
	s_nop 1
	v_add_f32_dpp v47, v47, v47 quad_perm:[2,3,0,1] row_mask:0xf bank_mask:0xf bound_ctrl:1
	s_nop 1
	v_add_f32_dpp v47, v47, v47 row_half_mirror row_mask:0xf bank_mask:0xf bound_ctrl:1
	s_nop 1
	v_add_f32_dpp v47, v47, v47 row_ror:8 row_mask:0xf bank_mask:0xf bound_ctrl:1
	s_nop 0
	v_readlane_b32 s2, v47, 16
	v_readlane_b32 s3, v47, 48
	v_readlane_b32 s26, v47, 0
	v_readlane_b32 s27, v47, 32
	v_mov_b32_e32 v50, s2
	v_mov_b32_e32 v51, s3
	v_pk_add_f32 v[50:51], s[26:27], v[50:51]
	s_nop 0
	v_add_f32_e32 v47, v50, v51
	v_rsq_f32_e32 v49, v47
	v_lshlrev_b32_e32 v47, 4, v94
	v_min_f32_e32 v49, 0x5368d4a5, v49
	v_mul_f32_e32 v50, v52, v49
	global_store_dword v[24:25], v50, off
	s_and_saveexec_b64 s[26:27], vcc
	v_add_u32_e32 v50, 0, v47
	v_add_u32_e32 v50, 0x12000, v50
	ds_write_b32 v50, v49
	s_or_b64 exec, exec, s[26:27]
	v_mov_b32_e32 v49, v227
	ds_read_b32 v50, v48 offset:1792
	s_waitcnt lgkmcnt(0)
	v_mul_f32_e32 v52, v50, v49
	v_mul_f32_e32 v49, v52, v52
	s_nop 1
	v_mov_b32_dpp v49, v49 quad_perm:[1,0,3,2] row_mask:0xf bank_mask:0xf bound_ctrl:1
	v_fmac_f32_e32 v49, v52, v52
	s_nop 1
	v_add_f32_dpp v49, v49, v49 quad_perm:[2,3,0,1] row_mask:0xf bank_mask:0xf bound_ctrl:1
	s_nop 1
	v_add_f32_dpp v49, v49, v49 row_half_mirror row_mask:0xf bank_mask:0xf bound_ctrl:1
	s_nop 1
	v_add_f32_dpp v49, v49, v49 row_ror:8 row_mask:0xf bank_mask:0xf bound_ctrl:1
	s_nop 0
	v_readlane_b32 s2, v49, 16
	v_readlane_b32 s3, v49, 48
	v_readlane_b32 s26, v49, 0
	v_readlane_b32 s27, v49, 32
	v_mov_b32_e32 v50, s2
	v_mov_b32_e32 v51, s3
	v_pk_add_f32 v[50:51], s[26:27], v[50:51]
	s_nop 0
	v_add_f32_e32 v49, v50, v51
	v_rsq_f32_e32 v49, v49
	s_nop 0
	v_min_f32_e32 v49, 0x5368d4a5, v49
	v_mul_f32_e32 v50, v52, v49
	global_store_dword v[24:25], v50, off offset:256
	s_and_saveexec_b64 s[26:27], vcc
	s_add_i32 s2, 0, 0x12000
	v_add_u32_e32 v50, s2, v47
	ds_write_b32 v50, v49 offset:4
	s_or_b64 exec, exec, s[26:27]
	v_mov_b32_e32 v49, v228
	ds_read_b32 v50, v48 offset:2048
	s_waitcnt lgkmcnt(0)
	v_mul_f32_e32 v52, v50, v49
	v_mul_f32_e32 v49, v52, v52
	s_nop 1
	v_mov_b32_dpp v49, v49 quad_perm:[1,0,3,2] row_mask:0xf bank_mask:0xf bound_ctrl:1
	v_fmac_f32_e32 v49, v52, v52
	s_nop 1
	v_add_f32_dpp v49, v49, v49 quad_perm:[2,3,0,1] row_mask:0xf bank_mask:0xf bound_ctrl:1
	s_nop 1
	v_add_f32_dpp v49, v49, v49 row_half_mirror row_mask:0xf bank_mask:0xf bound_ctrl:1
	s_nop 1
	v_add_f32_dpp v49, v49, v49 row_ror:8 row_mask:0xf bank_mask:0xf bound_ctrl:1
	s_nop 0
	v_readlane_b32 s2, v49, 16
	v_readlane_b32 s3, v49, 48
	v_readlane_b32 s26, v49, 0
	v_readlane_b32 s27, v49, 32
	v_mov_b32_e32 v50, s2
	v_mov_b32_e32 v51, s3
	v_pk_add_f32 v[50:51], s[26:27], v[50:51]
	s_nop 0
	v_add_f32_e32 v49, v50, v51
	v_rsq_f32_e32 v49, v49
	s_nop 0
	v_min_f32_e32 v49, 0x5368d4a5, v49
	v_mul_f32_e32 v50, v52, v49
	global_store_dword v[24:25], v50, off offset:512
	s_and_saveexec_b64 s[26:27], vcc
	s_add_i32 s2, 0, 0x12000
	v_add_u32_e32 v50, s2, v47
	ds_write_b32 v50, v49 offset:8
	s_or_b64 exec, exec, s[26:27]
	v_mov_b32_e32 v49, v229
	ds_read_b32 v48, v48 offset:2304
	s_waitcnt lgkmcnt(0)
	v_mul_f32_e32 v50, v48, v49
	v_mul_f32_e32 v48, v50, v50
	s_nop 1
	v_mov_b32_dpp v48, v48 quad_perm:[1,0,3,2] row_mask:0xf bank_mask:0xf bound_ctrl:1
	v_fmac_f32_e32 v48, v50, v50
	s_nop 1
	v_add_f32_dpp v48, v48, v48 quad_perm:[2,3,0,1] row_mask:0xf bank_mask:0xf bound_ctrl:1
	s_nop 1
	v_add_f32_dpp v48, v48, v48 row_half_mirror row_mask:0xf bank_mask:0xf bound_ctrl:1
	s_nop 1
	v_add_f32_dpp v48, v48, v48 row_ror:8 row_mask:0xf bank_mask:0xf bound_ctrl:1
	s_nop 0
	v_readlane_b32 s2, v48, 16
	v_readlane_b32 s3, v48, 48
	v_readlane_b32 s26, v48, 0
	v_readlane_b32 s27, v48, 32
	v_mov_b32_e32 v48, s2
	v_mov_b32_e32 v49, s3
	v_pk_add_f32 v[48:49], s[26:27], v[48:49]
	s_nop 0
	v_add_f32_e32 v48, v48, v49
	v_rsq_f32_e32 v48, v48
	s_nop 0
	v_min_f32_e32 v48, 0x5368d4a5, v48
	v_mul_f32_e32 v49, v50, v48
	global_store_dword v[24:25], v49, off offset:768
	s_and_saveexec_b64 s[26:27], vcc
	s_add_i32 s2, 0, 0x12000
	v_add_u32_e32 v24, s2, v47
	ds_write_b32 v24, v48 offset:12
	s_or_b64 exec, exec, s[26:27]
	v_or_b32_e32 v46, 1, v46
	s_movk_i32 s2, 0x1200
	v_mul_lo_u32 v24, v46, s2
	v_ashrrev_i32_e32 v47, 31, v46
	v_add3_u32 v24, 0, v24, v0
	v_lshl_add_u64 v[48:49], s[34:35], 0, v[46:47]
	v_lshlrev_b32_e32 v0, 4, v46
	v_mov_b32_e32 v46, v226
	ds_read_b32 v25, v24 offset:1536
	v_lshlrev_b64 v[48:49], 10, v[48:49]
	v_lshl_add_u64 v[4:5], v[4:5], 0, v[48:49]
	s_waitcnt lgkmcnt(0)
	v_mul_f32_e32 v48, v25, v46
	v_mul_f32_e32 v25, v48, v48
	s_nop 1
	v_mov_b32_dpp v25, v25 quad_perm:[1,0,3,2] row_mask:0xf bank_mask:0xf bound_ctrl:1
	v_fmac_f32_e32 v25, v48, v48
	s_nop 1
	v_add_f32_dpp v25, v25, v25 quad_perm:[2,3,0,1] row_mask:0xf bank_mask:0xf bound_ctrl:1
	s_nop 1
	v_add_f32_dpp v25, v25, v25 row_half_mirror row_mask:0xf bank_mask:0xf bound_ctrl:1
	s_nop 1
	v_add_f32_dpp v25, v25, v25 row_ror:8 row_mask:0xf bank_mask:0xf bound_ctrl:1
	s_nop 0
	v_readlane_b32 s2, v25, 16
	v_readlane_b32 s3, v25, 48
	v_readlane_b32 s26, v25, 0
	v_readlane_b32 s27, v25, 32
	v_mov_b32_e32 v46, s2
	v_mov_b32_e32 v47, s3
	v_pk_add_f32 v[46:47], s[26:27], v[46:47]
	s_nop 0
	v_add_f32_e32 v25, v46, v47
	v_rsq_f32_e32 v25, v25
	s_nop 0
	v_min_f32_e32 v25, 0x5368d4a5, v25
	v_mul_f32_e32 v46, v48, v25
	global_store_dword v[4:5], v46, off
	s_and_saveexec_b64 s[26:27], vcc
	v_add_u32_e32 v46, 0, v0
	v_add_u32_e32 v46, 0x12000, v46
	ds_write_b32 v46, v25
	s_or_b64 exec, exec, s[26:27]
	v_mov_b32_e32 v25, v227
	ds_read_b32 v46, v24 offset:1792
	s_waitcnt lgkmcnt(0)
	v_mul_f32_e32 v48, v46, v25
	v_mul_f32_e32 v25, v48, v48
	s_nop 1
	v_mov_b32_dpp v25, v25 quad_perm:[1,0,3,2] row_mask:0xf bank_mask:0xf bound_ctrl:1
	v_fmac_f32_e32 v25, v48, v48
	s_nop 1
	v_add_f32_dpp v25, v25, v25 quad_perm:[2,3,0,1] row_mask:0xf bank_mask:0xf bound_ctrl:1
	s_nop 1
	v_add_f32_dpp v25, v25, v25 row_half_mirror row_mask:0xf bank_mask:0xf bound_ctrl:1
	s_nop 1
	v_add_f32_dpp v25, v25, v25 row_ror:8 row_mask:0xf bank_mask:0xf bound_ctrl:1
	s_nop 0
	v_readlane_b32 s2, v25, 16
	v_readlane_b32 s3, v25, 48
	v_readlane_b32 s26, v25, 0
	v_readlane_b32 s27, v25, 32
	v_mov_b32_e32 v46, s2
	v_mov_b32_e32 v47, s3
	v_pk_add_f32 v[46:47], s[26:27], v[46:47]
	s_nop 0
	v_add_f32_e32 v25, v46, v47
	v_rsq_f32_e32 v25, v25
	s_nop 0
	v_min_f32_e32 v25, 0x5368d4a5, v25
	v_mul_f32_e32 v46, v48, v25
	global_store_dword v[4:5], v46, off offset:256
	s_and_saveexec_b64 s[26:27], vcc
	s_add_i32 s2, 0, 0x12000
	v_add_u32_e32 v46, s2, v0
	ds_write_b32 v46, v25 offset:4
	s_or_b64 exec, exec, s[26:27]
	v_mov_b32_e32 v25, v228
	ds_read_b32 v46, v24 offset:2048
	s_waitcnt lgkmcnt(0)
	v_mul_f32_e32 v48, v46, v25
	v_mul_f32_e32 v25, v48, v48
	s_nop 1
	v_mov_b32_dpp v25, v25 quad_perm:[1,0,3,2] row_mask:0xf bank_mask:0xf bound_ctrl:1
	v_fmac_f32_e32 v25, v48, v48
	s_nop 1
	v_add_f32_dpp v25, v25, v25 quad_perm:[2,3,0,1] row_mask:0xf bank_mask:0xf bound_ctrl:1
	s_nop 1
	v_add_f32_dpp v25, v25, v25 row_half_mirror row_mask:0xf bank_mask:0xf bound_ctrl:1
	s_nop 1
	v_add_f32_dpp v25, v25, v25 row_ror:8 row_mask:0xf bank_mask:0xf bound_ctrl:1
	s_nop 0
	v_readlane_b32 s2, v25, 16
	v_readlane_b32 s3, v25, 48
	v_readlane_b32 s26, v25, 0
	v_readlane_b32 s27, v25, 32
	v_mov_b32_e32 v46, s2
	v_mov_b32_e32 v47, s3
	v_pk_add_f32 v[46:47], s[26:27], v[46:47]
	s_nop 0
	v_add_f32_e32 v25, v46, v47
	v_rsq_f32_e32 v25, v25
	s_nop 0
	v_min_f32_e32 v25, 0x5368d4a5, v25
	v_mul_f32_e32 v46, v48, v25
	global_store_dword v[4:5], v46, off offset:512
	s_and_saveexec_b64 s[26:27], vcc
	s_add_i32 s2, 0, 0x12000
	v_add_u32_e32 v46, s2, v0
	ds_write_b32 v46, v25 offset:8
	s_or_b64 exec, exec, s[26:27]
	v_mov_b32_e32 v2, v229
	ds_read_b32 v3, v24 offset:2304
	s_waitcnt lgkmcnt(0)
	v_mul_f32_e32 v24, v3, v2
	v_mul_f32_e32 v2, v24, v24
	s_nop 1
	v_mov_b32_dpp v2, v2 quad_perm:[1,0,3,2] row_mask:0xf bank_mask:0xf bound_ctrl:1
	v_fmac_f32_e32 v2, v24, v24
	s_nop 1
	v_add_f32_dpp v2, v2, v2 quad_perm:[2,3,0,1] row_mask:0xf bank_mask:0xf bound_ctrl:1
	s_nop 1
	v_add_f32_dpp v2, v2, v2 row_half_mirror row_mask:0xf bank_mask:0xf bound_ctrl:1
	s_nop 1
	v_add_f32_dpp v2, v2, v2 row_ror:8 row_mask:0xf bank_mask:0xf bound_ctrl:1
	s_nop 0
	v_readlane_b32 s2, v2, 16
	v_readlane_b32 s3, v2, 48
	v_readlane_b32 s26, v2, 0
	v_readlane_b32 s27, v2, 32
	v_mov_b32_e32 v2, s2
	v_mov_b32_e32 v3, s3
	v_pk_add_f32 v[2:3], s[26:27], v[2:3]
	s_nop 0
	v_add_f32_e32 v2, v2, v3
	v_rsq_f32_e32 v2, v2
	s_nop 0
	v_min_f32_e32 v2, 0x5368d4a5, v2
	v_mul_f32_e32 v3, v24, v2
	global_store_dword v[4:5], v3, off offset:768
	s_and_saveexec_b64 s[26:27], vcc
	s_add_i32 s2, 0, 0x12000
	v_add_u32_e32 v0, s2, v0
	ds_write_b32 v0, v2 offset:12
	s_or_b64 exec, exec, s[26:27]
	s_cmp_lt_i32 s44, 0
	s_waitcnt lgkmcnt(0)
	s_barrier
	s_cbranch_scc1 .LBB0_935
	v_readlane_b32 s2, v252, 18
	v_readlane_b32 s3, v252, 19
	s_mov_b64 s[76:77], s[40:41]
	s_lshl_b32 s72, s44, 4
	s_mul_i32 s26, s72, 0x900
	s_add_u32 s42, s2, s26
	s_addc_u32 s43, s3, 0
	s_sub_u32 s46, s42, 0x24000
	s_subb_u32 s47, s43, 0
	s_movk_i32 s49, 0x900
	s_cmpk_lt_i32 s44, 0x400
	s_cbranch_scc0 .Lpi_ctx
	s_and_b32 s48, s72, 0xfff
	v_cmp_gt_u32_e32 vcc, 96, v27
	v_lshlrev_b32_e32 v0, 1, v27
	v_subrev_u32_e32 v2, 96, v27
	v_cndmask_b32_e32 v0, v2, v0, vcc
	v_mul_u32_u24_e32 v0, 0x556, v0
	v_lshrrev_b32_e32 v0, 16, v0
	v_and_b32_e32 v2, 1, v0
	v_lshl_add_u32 v2, v2, 1, -1
	v_lshrrev_b32_e32 v0, 1, v0
	v_mul_u32_u24_e32 v0, 6, v0
	v_lshlrev_b32_e32 v2, v0, v2
	v_lshlrev_b32_e64 v3, v0, 64
	v_add_u32_e32 v3, -1, v3
	v_mul_u32_u24_e32 v4, 0x480, v29
	v_add_lshl_u32 v4, v4, v6, 1
	global_load_dwordx2 v[58:59], v4, s[42:43]
	v_add_u32_e32 v5, 64, v2
	v_mad_u32_u24 v4, v5, s49, v4
	v_add_u32_e32 v5, s48, v29
	v_and_b32_e32 v5, v5, v3
	v_add_u32_e32 v5, v5, v2
	v_cmp_le_u32_e32 vcc, v5, v3
	v_mov_b32_e32 v60, 0
	v_mov_b32_e32 v61, 0
	s_and_saveexec_b64 s[26:27], vcc
	global_load_dwordx2 v[60:61], v4, s[46:47]
	s_mov_b64 exec, s[26:27]
	v_cmp_gt_u32_e32 vcc, 96, v28
	v_lshlrev_b32_e32 v0, 1, v28
	v_subrev_u32_e32 v2, 96, v28
	v_cndmask_b32_e32 v0, v2, v0, vcc
	v_mul_u32_u24_e32 v0, 0x556, v0
	v_lshrrev_b32_e32 v0, 16, v0
	v_and_b32_e32 v2, 1, v0
	v_lshl_add_u32 v2, v2, 1, -1
	v_lshrrev_b32_e32 v0, 1, v0
	v_mul_u32_u24_e32 v0, 6, v0
	v_lshlrev_b32_e32 v2, v0, v2
	v_lshlrev_b32_e64 v3, v0, 64
	v_add_u32_e32 v3, -1, v3
	v_mul_u32_u24_e32 v4, 0x480, v31
	v_add_lshl_u32 v4, v4, v8, 1
	global_load_dwordx2 v[62:63], v4, s[42:43]
	v_add_u32_e32 v5, 64, v2
	v_mad_u32_u24 v4, v5, s49, v4
	v_add_u32_e32 v5, s48, v31
	v_and_b32_e32 v5, v5, v3
	v_add_u32_e32 v5, v5, v2
	v_cmp_le_u32_e32 vcc, v5, v3
	v_mov_b32_e32 v64, 0
	v_mov_b32_e32 v65, 0
	s_and_saveexec_b64 s[26:27], vcc
	global_load_dwordx2 v[64:65], v4, s[46:47]
	s_mov_b64 exec, s[26:27]
	v_cmp_gt_u32_e32 vcc, 96, v30
	v_lshlrev_b32_e32 v0, 1, v30
	v_subrev_u32_e32 v2, 96, v30
	v_cndmask_b32_e32 v0, v2, v0, vcc
	v_mul_u32_u24_e32 v0, 0x556, v0
	v_lshrrev_b32_e32 v0, 16, v0
	v_and_b32_e32 v2, 1, v0
	v_lshl_add_u32 v2, v2, 1, -1
	v_lshrrev_b32_e32 v0, 1, v0
	v_mul_u32_u24_e32 v0, 6, v0
	v_lshlrev_b32_e32 v2, v0, v2
	v_lshlrev_b32_e64 v3, v0, 64
	v_add_u32_e32 v3, -1, v3
	v_mul_u32_u24_e32 v4, 0x480, v33
	v_add_lshl_u32 v4, v4, v10, 1
	global_load_dwordx2 v[66:67], v4, s[42:43]
	v_add_u32_e32 v5, 64, v2
	v_mad_u32_u24 v4, v5, s49, v4
	v_add_u32_e32 v5, s48, v33
	v_and_b32_e32 v5, v5, v3
	v_add_u32_e32 v5, v5, v2
	v_cmp_le_u32_e32 vcc, v5, v3
	v_mov_b32_e32 v68, 0
	v_mov_b32_e32 v69, 0
	s_and_saveexec_b64 s[26:27], vcc
	global_load_dwordx2 v[68:69], v4, s[46:47]
	s_mov_b64 exec, s[26:27]
	v_cmp_gt_u32_e32 vcc, 96, v32
	v_lshlrev_b32_e32 v0, 1, v32
	v_subrev_u32_e32 v2, 96, v32
	v_cndmask_b32_e32 v0, v2, v0, vcc
	v_mul_u32_u24_e32 v0, 0x556, v0
	v_lshrrev_b32_e32 v0, 16, v0
	v_and_b32_e32 v2, 1, v0
	v_lshl_add_u32 v2, v2, 1, -1
	v_lshrrev_b32_e32 v0, 1, v0
	v_mul_u32_u24_e32 v0, 6, v0
	v_lshlrev_b32_e32 v2, v0, v2
	v_lshlrev_b32_e64 v3, v0, 64
	v_add_u32_e32 v3, -1, v3
	v_mul_u32_u24_e32 v4, 0x480, v35
	v_add_lshl_u32 v4, v4, v12, 1
	global_load_dwordx2 v[70:71], v4, s[42:43]
	v_add_u32_e32 v5, 64, v2
	v_mad_u32_u24 v4, v5, s49, v4
	v_add_u32_e32 v5, s48, v35
	v_and_b32_e32 v5, v5, v3
	v_add_u32_e32 v5, v5, v2
	v_cmp_le_u32_e32 vcc, v5, v3
	v_mov_b32_e32 v72, 0
	v_mov_b32_e32 v73, 0
	s_and_saveexec_b64 s[26:27], vcc
	global_load_dwordx2 v[72:73], v4, s[46:47]
	s_mov_b64 exec, s[26:27]
	v_cmp_gt_u32_e32 vcc, 96, v34
	v_lshlrev_b32_e32 v0, 1, v34
	v_subrev_u32_e32 v2, 96, v34
	v_cndmask_b32_e32 v0, v2, v0, vcc
	v_mul_u32_u24_e32 v0, 0x556, v0
	v_lshrrev_b32_e32 v0, 16, v0
	v_and_b32_e32 v2, 1, v0
	v_lshl_add_u32 v2, v2, 1, -1
	v_lshrrev_b32_e32 v0, 1, v0
	v_mul_u32_u24_e32 v0, 6, v0
	v_lshlrev_b32_e32 v2, v0, v2
	v_lshlrev_b32_e64 v3, v0, 64
	v_add_u32_e32 v3, -1, v3
	v_mul_u32_u24_e32 v4, 0x480, v37
	v_add_lshl_u32 v4, v4, v14, 1
	global_load_dwordx2 v[74:75], v4, s[42:43]
	v_add_u32_e32 v5, 64, v2
	v_mad_u32_u24 v4, v5, s49, v4
	v_add_u32_e32 v5, s48, v37
	v_and_b32_e32 v5, v5, v3
	v_add_u32_e32 v5, v5, v2
	v_cmp_le_u32_e32 vcc, v5, v3
	v_mov_b32_e32 v76, 0
	v_mov_b32_e32 v77, 0
	s_and_saveexec_b64 s[26:27], vcc
	global_load_dwordx2 v[76:77], v4, s[46:47]
	s_mov_b64 exec, s[26:27]
	v_cmp_gt_u32_e32 vcc, 96, v36
	v_lshlrev_b32_e32 v0, 1, v36
	v_subrev_u32_e32 v2, 96, v36
	v_cndmask_b32_e32 v0, v2, v0, vcc
	v_mul_u32_u24_e32 v0, 0x556, v0
	v_lshrrev_b32_e32 v0, 16, v0
	v_and_b32_e32 v2, 1, v0
	v_lshl_add_u32 v2, v2, 1, -1
	v_lshrrev_b32_e32 v0, 1, v0
	v_mul_u32_u24_e32 v0, 6, v0
	v_lshlrev_b32_e32 v2, v0, v2
	v_lshlrev_b32_e64 v3, v0, 64
	v_add_u32_e32 v3, -1, v3
	v_mul_u32_u24_e32 v4, 0x480, v39
	v_add_lshl_u32 v4, v4, v16, 1
	global_load_dwordx2 v[78:79], v4, s[42:43]
	v_add_u32_e32 v5, 64, v2
	v_mad_u32_u24 v4, v5, s49, v4
	v_add_u32_e32 v5, s48, v39
	v_and_b32_e32 v5, v5, v3
	v_add_u32_e32 v5, v5, v2
	v_cmp_le_u32_e32 vcc, v5, v3
	v_mov_b32_e32 v80, 0
	v_mov_b32_e32 v81, 0
	s_and_saveexec_b64 s[26:27], vcc
	global_load_dwordx2 v[80:81], v4, s[46:47]
	s_mov_b64 exec, s[26:27]
	v_cmp_gt_u32_e32 vcc, 96, v38
	v_lshlrev_b32_e32 v0, 1, v38
	v_subrev_u32_e32 v2, 96, v38
	v_cndmask_b32_e32 v0, v2, v0, vcc
	v_mul_u32_u24_e32 v0, 0x556, v0
	v_lshrrev_b32_e32 v0, 16, v0
	v_and_b32_e32 v2, 1, v0
	v_lshl_add_u32 v2, v2, 1, -1
	v_lshrrev_b32_e32 v0, 1, v0
	v_mul_u32_u24_e32 v0, 6, v0
	v_lshlrev_b32_e32 v2, v0, v2
	v_lshlrev_b32_e64 v3, v0, 64
	v_add_u32_e32 v3, -1, v3
	v_mul_u32_u24_e32 v4, 0x480, v41
	v_add_lshl_u32 v4, v4, v18, 1
	global_load_dwordx2 v[82:83], v4, s[42:43]
	v_add_u32_e32 v5, 64, v2
	v_mad_u32_u24 v4, v5, s49, v4
	v_add_u32_e32 v5, s48, v41
	v_and_b32_e32 v5, v5, v3
	v_add_u32_e32 v5, v5, v2
	v_cmp_le_u32_e32 vcc, v5, v3
	v_mov_b32_e32 v84, 0
	v_mov_b32_e32 v85, 0
	s_and_saveexec_b64 s[26:27], vcc
	global_load_dwordx2 v[84:85], v4, s[46:47]
	s_mov_b64 exec, s[26:27]
	v_cmp_gt_u32_e32 vcc, 96, v40
	v_lshlrev_b32_e32 v0, 1, v40
	v_subrev_u32_e32 v2, 96, v40
	v_cndmask_b32_e32 v0, v2, v0, vcc
	v_mul_u32_u24_e32 v0, 0x556, v0
	v_lshrrev_b32_e32 v0, 16, v0
	v_and_b32_e32 v2, 1, v0
	v_lshl_add_u32 v2, v2, 1, -1
	v_lshrrev_b32_e32 v0, 1, v0
	v_mul_u32_u24_e32 v0, 6, v0
	v_lshlrev_b32_e32 v2, v0, v2
	v_lshlrev_b32_e64 v3, v0, 64
	v_add_u32_e32 v3, -1, v3
	v_mul_u32_u24_e32 v4, 0x480, v43
	v_add_lshl_u32 v4, v4, v20, 1
	global_load_dwordx2 v[86:87], v4, s[42:43]
	v_add_u32_e32 v5, 64, v2
	v_mad_u32_u24 v4, v5, s49, v4
	v_add_u32_e32 v5, s48, v43
	v_and_b32_e32 v5, v5, v3
	v_add_u32_e32 v5, v5, v2
	v_cmp_le_u32_e32 vcc, v5, v3
	v_mov_b32_e32 v88, 0
	v_mov_b32_e32 v89, 0
	s_and_saveexec_b64 s[26:27], vcc
	global_load_dwordx2 v[88:89], v4, s[46:47]
	s_mov_b64 exec, s[26:27]
	v_cmp_gt_u32_e32 vcc, 96, v42
	v_lshlrev_b32_e32 v0, 1, v42
	v_subrev_u32_e32 v2, 96, v42
	v_cndmask_b32_e32 v0, v2, v0, vcc
	v_mul_u32_u24_e32 v0, 0x556, v0
	v_lshrrev_b32_e32 v0, 16, v0
	v_and_b32_e32 v2, 1, v0
	v_lshl_add_u32 v2, v2, 1, -1
	v_lshrrev_b32_e32 v0, 1, v0
	v_mul_u32_u24_e32 v0, 6, v0
	v_lshlrev_b32_e32 v2, v0, v2
	v_lshlrev_b32_e64 v3, v0, 64
	v_add_u32_e32 v3, -1, v3
	v_mul_u32_u24_e32 v4, 0x480, v45
	v_add_lshl_u32 v4, v4, v22, 1
	global_load_dwordx2 v[90:91], v4, s[42:43]
	v_add_u32_e32 v5, 64, v2
	v_mad_u32_u24 v4, v5, s49, v4
	v_add_u32_e32 v5, s48, v45
	v_and_b32_e32 v5, v5, v3
	v_add_u32_e32 v5, v5, v2
	v_cmp_le_u32_e32 vcc, v5, v3
	v_mov_b32_e32 v92, 0
	v_mov_b32_e32 v93, 0
	s_and_saveexec_b64 s[26:27], vcc
	global_load_dwordx2 v[92:93], v4, s[46:47]
	s_mov_b64 exec, s[26:27]
	s_branch .Lpi_done

.Lpi0_done_early:
	s_mov_b32 s2, 0x38e38e39
	v_mov_b32_e32 v190, v232
	v_mul_hi_u32 v191, v190, s2
	v_lshrrev_b32_e32 v191, 6, v191
	v_mul_u32_u24_e32 v191, 0x120, v191
	v_sub_u32_e32 v190, v190, v191
	v_lshlrev_b32_e32 v190, 4, v190
	global_load_dwordx4 v[190:193], v190, s[40:41]
	v_add_u32_e32 v194, 0x200, v232
	v_mul_hi_u32 v195, v194, s2
	v_lshrrev_b32_e32 v195, 6, v195
	v_mul_u32_u24_e32 v195, 0x120, v195
	v_sub_u32_e32 v194, v194, v195
	v_lshlrev_b32_e32 v194, 4, v194
	global_load_dwordx4 v[194:197], v194, s[40:41]
	v_add_u32_e32 v198, 0x400, v232
	v_mul_hi_u32 v199, v198, s2
	v_lshrrev_b32_e32 v199, 6, v199
	v_mul_u32_u24_e32 v199, 0x120, v199
	v_sub_u32_e32 v198, v198, v199
	v_lshlrev_b32_e32 v198, 4, v198
	global_load_dwordx4 v[198:201], v198, s[40:41]
	v_add_u32_e32 v202, 0x600, v232
	v_mul_hi_u32 v203, v202, s2
	v_lshrrev_b32_e32 v203, 6, v203
	v_mul_u32_u24_e32 v203, 0x120, v203
	v_sub_u32_e32 v202, v202, v203
	v_lshlrev_b32_e32 v202, 4, v202
	global_load_dwordx4 v[202:205], v202, s[40:41]
	v_add_u32_e32 v206, 0x800, v232
	v_mul_hi_u32 v207, v206, s2
	v_lshrrev_b32_e32 v207, 6, v207
	v_mul_u32_u24_e32 v207, 0x120, v207
	v_sub_u32_e32 v206, v206, v207
	v_lshlrev_b32_e32 v206, 4, v206
	global_load_dwordx4 v[206:209], v206, s[40:41]
	v_add_u32_e32 v210, 0xa00, v232
	v_mul_hi_u32 v211, v210, s2
	v_lshrrev_b32_e32 v211, 6, v211
	v_mul_u32_u24_e32 v211, 0x120, v211
	v_sub_u32_e32 v210, v210, v211
	v_lshlrev_b32_e32 v210, 4, v210
	global_load_dwordx4 v[210:213], v210, s[40:41]
	v_add_u32_e32 v214, 0xc00, v232
	v_mul_hi_u32 v215, v214, s2
	v_lshrrev_b32_e32 v215, 6, v215
	v_mul_u32_u24_e32 v215, 0x120, v215
	v_sub_u32_e32 v214, v214, v215
	v_lshlrev_b32_e32 v214, 4, v214
	global_load_dwordx4 v[214:217], v214, s[40:41]
	v_add_u32_e32 v218, 0xe00, v232
	v_mul_hi_u32 v219, v218, s2
	v_lshrrev_b32_e32 v219, 6, v219
	v_mul_u32_u24_e32 v219, 0x120, v219
	v_sub_u32_e32 v218, v218, v219
	v_lshlrev_b32_e32 v218, 4, v218
	global_load_dwordx4 v[218:221], v218, s[40:41]
	v_add_u32_e32 v222, 0x1000, v232
	v_mul_hi_u32 v223, v222, s2
	v_lshrrev_b32_e32 v223, 6, v223
	v_mul_u32_u24_e32 v223, 0x120, v223
	v_sub_u32_e32 v222, v222, v223
	v_lshlrev_b32_e32 v222, 4, v222
	global_load_dwordx4 v[222:225], v222, s[40:41]
	v_readlane_b32 s2, v250, 60
	v_and_b32_e32 v226, 63, v232
	s_nop 1
	v_or_b32_e32 v226, s2, v226
	v_readlane_b32 s2, v251, 14
	v_readlane_b32 s3, v251, 15
	v_lshlrev_b32_e32 v226, 2, v226
	s_nop 4
	global_load_dword v227, v226, s[2:3] offset:256
	global_load_dword v228, v226, s[2:3] offset:512
	global_load_dword v229, v226, s[2:3] offset:768
	global_load_dword v226, v226, s[2:3]
	s_mov_b32 s31, s30

.LBB0_1675:
	s_or_b64 exec, exec, s[26:27]
	v_and_b32_e32 v44, 63, v26
	v_readlane_b32 s2, v250, 60
	v_readlane_b32 s4, v251, 8
	v_readlane_b32 s10, v251, 14
	v_or_b32_e32 v2, s2, v44
	v_ashrrev_i32_e32 v3, 31, v2
	v_readlane_b32 s11, v251, 15
	s_waitcnt lgkmcnt(0)
	s_barrier
	v_lshl_add_u64 v[2:3], v[2:3], 2, s[10:11]
	v_mov_b32_e32 v47, v226
	v_ashrrev_i32_e32 v46, 5, v26
	v_and_b32_e32 v94, -2, v46
	s_movk_i32 s2, 0x1200
	v_lshlrev_b32_e32 v0, 2, v44
	v_mul_lo_u32 v4, v94, s2
	v_add3_u32 v48, 0, v4, v0
	ds_read_b32 v49, v48 offset:1536
	v_readlane_b32 s3, v250, 61
	v_readlane_b32 s2, v252, 20
	v_readlane_b32 s3, v252, 21
	s_ashr_i32 s35, s34, 31
	s_lshl_b64 s[34:35], s[34:35], 4
	v_lshl_add_u64 v[4:5], s[2:3], 0, v[0:1]
	v_ashrrev_i32_e32 v95, 31, v94
	v_lshl_add_u64 v[24:25], s[34:35], 0, v[94:95]
	v_lshlrev_b64 v[24:25], 10, v[24:25]
	v_cmp_eq_u32_e32 vcc, 0, v44
	v_lshl_add_u64 v[24:25], v[4:5], 0, v[24:25]
	v_readlane_b32 s5, v251, 9
	v_readlane_b32 s6, v251, 10
	v_readlane_b32 s7, v251, 11
	v_readlane_b32 s8, v251, 12
	v_readlane_b32 s9, v251, 13
	v_readlane_b32 s12, v251, 16
	v_readlane_b32 s13, v251, 17
	v_readlane_b32 s14, v251, 18
	v_readlane_b32 s15, v251, 19
	v_readlane_b32 s16, v251, 20
	v_readlane_b32 s17, v251, 21
	v_readlane_b32 s18, v251, 22
	v_readlane_b32 s19, v251, 23
	s_waitcnt lgkmcnt(0)
	v_mul_f32_e32 v52, v49, v47
	v_mul_f32_e32 v47, v52, v52
	s_nop 1
	v_mov_b32_dpp v47, v47 quad_perm:[1,0,3,2] row_mask:0xf bank_mask:0xf bound_ctrl:1
	v_fmac_f32_e32 v47, v52, v52
	s_nop 1
	v_add_f32_dpp v47, v47, v47 quad_perm:[2,3,0,1] row_mask:0xf bank_mask:0xf bound_ctrl:1
	s_nop 1
	v_add_f32_dpp v47, v47, v47 row_half_mirror row_mask:0xf bank_mask:0xf bound_ctrl:1
	s_nop 1
	v_add_f32_dpp v47, v47, v47 row_ror:8 row_mask:0xf bank_mask:0xf bound_ctrl:1
	s_nop 0
	v_readlane_b32 s2, v47, 16
	v_readlane_b32 s3, v47, 48
	v_readlane_b32 s26, v47, 0
	v_readlane_b32 s27, v47, 32
	v_mov_b32_e32 v50, s2
	v_mov_b32_e32 v51, s3
	v_pk_add_f32 v[50:51], s[26:27], v[50:51]
	s_nop 0
	v_add_f32_e32 v47, v50, v51
	v_rsq_f32_e32 v49, v47
	v_lshlrev_b32_e32 v47, 4, v94
	v_min_f32_e32 v49, 0x5368d4a5, v49
	v_mul_f32_e32 v50, v52, v49
	global_store_dword v[24:25], v50, off
	s_and_saveexec_b64 s[26:27], vcc
	v_add_u32_e32 v50, 0, v47
	v_add_u32_e32 v50, 0x12000, v50
	ds_write_b32 v50, v49
	s_or_b64 exec, exec, s[26:27]
	v_mov_b32_e32 v49, v227
	ds_read_b32 v50, v48 offset:1792
	s_waitcnt lgkmcnt(0)
	v_mul_f32_e32 v52, v50, v49
	v_mul_f32_e32 v49, v52, v52
	s_nop 1
	v_mov_b32_dpp v49, v49 quad_perm:[1,0,3,2] row_mask:0xf bank_mask:0xf bound_ctrl:1
	v_fmac_f32_e32 v49, v52, v52
	s_nop 1
	v_add_f32_dpp v49, v49, v49 quad_perm:[2,3,0,1] row_mask:0xf bank_mask:0xf bound_ctrl:1
	s_nop 1
	v_add_f32_dpp v49, v49, v49 row_half_mirror row_mask:0xf bank_mask:0xf bound_ctrl:1
	s_nop 1
	v_add_f32_dpp v49, v49, v49 row_ror:8 row_mask:0xf bank_mask:0xf bound_ctrl:1
	s_nop 0
	v_readlane_b32 s2, v49, 16
	v_readlane_b32 s3, v49, 48
	v_readlane_b32 s26, v49, 0
	v_readlane_b32 s27, v49, 32
	v_mov_b32_e32 v50, s2
	v_mov_b32_e32 v51, s3
	v_pk_add_f32 v[50:51], s[26:27], v[50:51]
	s_nop 0
	v_add_f32_e32 v49, v50, v51
	v_rsq_f32_e32 v49, v49
	s_nop 0
	v_min_f32_e32 v49, 0x5368d4a5, v49
	v_mul_f32_e32 v50, v52, v49
	global_store_dword v[24:25], v50, off offset:256
	s_and_saveexec_b64 s[26:27], vcc
	s_add_i32 s2, 0, 0x12000
	v_add_u32_e32 v50, s2, v47
	ds_write_b32 v50, v49 offset:4
	s_or_b64 exec, exec, s[26:27]
	v_mov_b32_e32 v49, v228
	ds_read_b32 v50, v48 offset:2048
	s_waitcnt lgkmcnt(0)
	v_mul_f32_e32 v52, v50, v49
	v_mul_f32_e32 v49, v52, v52
	s_nop 1
	v_mov_b32_dpp v49, v49 quad_perm:[1,0,3,2] row_mask:0xf bank_mask:0xf bound_ctrl:1
	v_fmac_f32_e32 v49, v52, v52
	s_nop 1
	v_add_f32_dpp v49, v49, v49 quad_perm:[2,3,0,1] row_mask:0xf bank_mask:0xf bound_ctrl:1
	s_nop 1
	v_add_f32_dpp v49, v49, v49 row_half_mirror row_mask:0xf bank_mask:0xf bound_ctrl:1
	s_nop 1
	v_add_f32_dpp v49, v49, v49 row_ror:8 row_mask:0xf bank_mask:0xf bound_ctrl:1
	s_nop 0
	v_readlane_b32 s2, v49, 16
	v_readlane_b32 s3, v49, 48
	v_readlane_b32 s26, v49, 0
	v_readlane_b32 s27, v49, 32
	v_mov_b32_e32 v50, s2
	v_mov_b32_e32 v51, s3
	v_pk_add_f32 v[50:51], s[26:27], v[50:51]
	s_nop 0
	v_add_f32_e32 v49, v50, v51
	v_rsq_f32_e32 v49, v49
	s_nop 0
	v_min_f32_e32 v49, 0x5368d4a5, v49
	v_mul_f32_e32 v50, v52, v49
	global_store_dword v[24:25], v50, off offset:512
	s_and_saveexec_b64 s[26:27], vcc
	s_add_i32 s2, 0, 0x12000
	v_add_u32_e32 v50, s2, v47
	ds_write_b32 v50, v49 offset:8
	s_or_b64 exec, exec, s[26:27]
	v_mov_b32_e32 v49, v229
	ds_read_b32 v48, v48 offset:2304
	s_waitcnt lgkmcnt(0)
	v_mul_f32_e32 v50, v48, v49
	v_mul_f32_e32 v48, v50, v50
	s_nop 1
	v_mov_b32_dpp v48, v48 quad_perm:[1,0,3,2] row_mask:0xf bank_mask:0xf bound_ctrl:1
	v_fmac_f32_e32 v48, v50, v50
	s_nop 1
	v_add_f32_dpp v48, v48, v48 quad_perm:[2,3,0,1] row_mask:0xf bank_mask:0xf bound_ctrl:1
	s_nop 1
	v_add_f32_dpp v48, v48, v48 row_half_mirror row_mask:0xf bank_mask:0xf bound_ctrl:1
	s_nop 1
	v_add_f32_dpp v48, v48, v48 row_ror:8 row_mask:0xf bank_mask:0xf bound_ctrl:1
	s_nop 0
	v_readlane_b32 s2, v48, 16
	v_readlane_b32 s3, v48, 48
	v_readlane_b32 s26, v48, 0
	v_readlane_b32 s27, v48, 32
	v_mov_b32_e32 v48, s2
	v_mov_b32_e32 v49, s3
	v_pk_add_f32 v[48:49], s[26:27], v[48:49]
	s_nop 0
	v_add_f32_e32 v48, v48, v49
	v_rsq_f32_e32 v48, v48
	s_nop 0
	v_min_f32_e32 v48, 0x5368d4a5, v48
	v_mul_f32_e32 v49, v50, v48
	global_store_dword v[24:25], v49, off offset:768
	s_and_saveexec_b64 s[26:27], vcc
	s_add_i32 s2, 0, 0x12000
	v_add_u32_e32 v24, s2, v47
	ds_write_b32 v24, v48 offset:12
	s_or_b64 exec, exec, s[26:27]
	v_or_b32_e32 v46, 1, v46
	s_movk_i32 s2, 0x1200
	v_mul_lo_u32 v24, v46, s2
	v_ashrrev_i32_e32 v47, 31, v46
	v_add3_u32 v24, 0, v24, v0
	v_lshl_add_u64 v[48:49], s[34:35], 0, v[46:47]
	v_lshlrev_b32_e32 v0, 4, v46
	v_mov_b32_e32 v46, v226
	ds_read_b32 v25, v24 offset:1536
	v_lshlrev_b64 v[48:49], 10, v[48:49]
	v_lshl_add_u64 v[4:5], v[4:5], 0, v[48:49]
	s_waitcnt lgkmcnt(0)
	v_mul_f32_e32 v48, v25, v46
	v_mul_f32_e32 v25, v48, v48
	s_nop 1
	v_mov_b32_dpp v25, v25 quad_perm:[1,0,3,2] row_mask:0xf bank_mask:0xf bound_ctrl:1
	v_fmac_f32_e32 v25, v48, v48
	s_nop 1
	v_add_f32_dpp v25, v25, v25 quad_perm:[2,3,0,1] row_mask:0xf bank_mask:0xf bound_ctrl:1
	s_nop 1
	v_add_f32_dpp v25, v25, v25 row_half_mirror row_mask:0xf bank_mask:0xf bound_ctrl:1
	s_nop 1
	v_add_f32_dpp v25, v25, v25 row_ror:8 row_mask:0xf bank_mask:0xf bound_ctrl:1
	s_nop 0
	v_readlane_b32 s2, v25, 16
	v_readlane_b32 s3, v25, 48
	v_readlane_b32 s26, v25, 0
	v_readlane_b32 s27, v25, 32
	v_mov_b32_e32 v46, s2
	v_mov_b32_e32 v47, s3
	v_pk_add_f32 v[46:47], s[26:27], v[46:47]
	s_nop 0
	v_add_f32_e32 v25, v46, v47
	v_rsq_f32_e32 v25, v25
	s_nop 0
	v_min_f32_e32 v25, 0x5368d4a5, v25
	v_mul_f32_e32 v46, v48, v25
	global_store_dword v[4:5], v46, off
	s_and_saveexec_b64 s[26:27], vcc
	v_add_u32_e32 v46, 0, v0
	v_add_u32_e32 v46, 0x12000, v46
	ds_write_b32 v46, v25
	s_or_b64 exec, exec, s[26:27]
	v_mov_b32_e32 v25, v227
	ds_read_b32 v46, v24 offset:1792
	s_waitcnt lgkmcnt(0)
	v_mul_f32_e32 v48, v46, v25
	v_mul_f32_e32 v25, v48, v48
	s_nop 1
	v_mov_b32_dpp v25, v25 quad_perm:[1,0,3,2] row_mask:0xf bank_mask:0xf bound_ctrl:1
	v_fmac_f32_e32 v25, v48, v48
	s_nop 1
	v_add_f32_dpp v25, v25, v25 quad_perm:[2,3,0,1] row_mask:0xf bank_mask:0xf bound_ctrl:1
	s_nop 1
	v_add_f32_dpp v25, v25, v25 row_half_mirror row_mask:0xf bank_mask:0xf bound_ctrl:1
	s_nop 1
	v_add_f32_dpp v25, v25, v25 row_ror:8 row_mask:0xf bank_mask:0xf bound_ctrl:1
	s_nop 0
	v_readlane_b32 s2, v25, 16
	v_readlane_b32 s3, v25, 48
	v_readlane_b32 s26, v25, 0
	v_readlane_b32 s27, v25, 32
	v_mov_b32_e32 v46, s2
	v_mov_b32_e32 v47, s3
	v_pk_add_f32 v[46:47], s[26:27], v[46:47]
	s_nop 0
	v_add_f32_e32 v25, v46, v47
	v_rsq_f32_e32 v25, v25
	s_nop 0
	v_min_f32_e32 v25, 0x5368d4a5, v25
	v_mul_f32_e32 v46, v48, v25
	global_store_dword v[4:5], v46, off offset:256
	s_and_saveexec_b64 s[26:27], vcc
	s_add_i32 s2, 0, 0x12000
	v_add_u32_e32 v46, s2, v0
	ds_write_b32 v46, v25 offset:4
	s_or_b64 exec, exec, s[26:27]
	v_mov_b32_e32 v25, v228
	ds_read_b32 v46, v24 offset:2048
	s_waitcnt lgkmcnt(0)
	v_mul_f32_e32 v48, v46, v25
	v_mul_f32_e32 v25, v48, v48
	s_nop 1
	v_mov_b32_dpp v25, v25 quad_perm:[1,0,3,2] row_mask:0xf bank_mask:0xf bound_ctrl:1
	v_fmac_f32_e32 v25, v48, v48
	s_nop 1
	v_add_f32_dpp v25, v25, v25 quad_perm:[2,3,0,1] row_mask:0xf bank_mask:0xf bound_ctrl:1
	s_nop 1
	v_add_f32_dpp v25, v25, v25 row_half_mirror row_mask:0xf bank_mask:0xf bound_ctrl:1
	s_nop 1
	v_add_f32_dpp v25, v25, v25 row_ror:8 row_mask:0xf bank_mask:0xf bound_ctrl:1
	s_nop 0
	v_readlane_b32 s2, v25, 16
	v_readlane_b32 s3, v25, 48
	v_readlane_b32 s26, v25, 0
	v_readlane_b32 s27, v25, 32
	v_mov_b32_e32 v46, s2
	v_mov_b32_e32 v47, s3
	v_pk_add_f32 v[46:47], s[26:27], v[46:47]
	s_nop 0
	v_add_f32_e32 v25, v46, v47
	v_rsq_f32_e32 v25, v25
	s_nop 0
	v_min_f32_e32 v25, 0x5368d4a5, v25
	v_mul_f32_e32 v46, v48, v25
	global_store_dword v[4:5], v46, off offset:512
	s_and_saveexec_b64 s[26:27], vcc
	s_add_i32 s2, 0, 0x12000
	v_add_u32_e32 v46, s2, v0
	ds_write_b32 v46, v25 offset:8
	s_or_b64 exec, exec, s[26:27]
	v_mov_b32_e32 v2, v229
	ds_read_b32 v3, v24 offset:2304
	s_waitcnt lgkmcnt(0)
	v_mul_f32_e32 v24, v3, v2
	v_mul_f32_e32 v2, v24, v24
	s_nop 1
	v_mov_b32_dpp v2, v2 quad_perm:[1,0,3,2] row_mask:0xf bank_mask:0xf bound_ctrl:1
	v_fmac_f32_e32 v2, v24, v24
	s_nop 1
	v_add_f32_dpp v2, v2, v2 quad_perm:[2,3,0,1] row_mask:0xf bank_mask:0xf bound_ctrl:1
	s_nop 1
	v_add_f32_dpp v2, v2, v2 row_half_mirror row_mask:0xf bank_mask:0xf bound_ctrl:1
	s_nop 1
	v_add_f32_dpp v2, v2, v2 row_ror:8 row_mask:0xf bank_mask:0xf bound_ctrl:1
	s_nop 0
	v_readlane_b32 s2, v2, 16
	v_readlane_b32 s3, v2, 48
	v_readlane_b32 s26, v2, 0
	v_readlane_b32 s27, v2, 32
	v_mov_b32_e32 v2, s2
	v_mov_b32_e32 v3, s3
	v_pk_add_f32 v[2:3], s[26:27], v[2:3]
	s_nop 0
	v_add_f32_e32 v2, v2, v3
	v_rsq_f32_e32 v2, v2
	s_nop 0
	v_min_f32_e32 v2, 0x5368d4a5, v2
	v_mul_f32_e32 v3, v24, v2
	global_store_dword v[4:5], v3, off offset:768
	s_and_saveexec_b64 s[26:27], vcc
	s_add_i32 s2, 0, 0x12000
	v_add_u32_e32 v0, s2, v0
	ds_write_b32 v0, v2 offset:12
	s_or_b64 exec, exec, s[26:27]
	s_cmp_lt_i32 s37, 0
	s_waitcnt lgkmcnt(0)
	s_barrier
	s_cbranch_scc1 .LBB0_1945
	v_readlane_b32 s2, v252, 18
	s_lshl_b32 s37, s37, 4
	v_readlane_b32 s3, v252, 19
	v_add_u32_e32 v2, s37, v29
	s_nop 0
	v_mov_b64_e32 v[4:5], s[2:3]
	s_movk_i32 s2, 0x900
	v_mad_i64_i32 v[4:5], s[26:27], v2, s2, v[4:5]
	v_lshl_add_u64 v[4:5], v[6:7], 1, v[4:5]
	global_load_dwordx2 v[58:59], v[4:5], off
	s_movk_i32 s2, 0x3fff
	v_cmp_lt_i32_e64 s[42:43], s2, v2
	s_movk_i32 s2, 0x5f
	v_cmp_lt_i32_e32 vcc, s2, v27
	s_and_saveexec_b64 s[44:45], s[42:43]
	s_xor_b64 s[44:45], exec, s[44:45]
	s_cbranch_execz .LBB0_1698
	s_and_saveexec_b64 s[26:27], vcc
	s_xor_b64 s[26:27], exec, s[26:27]
	v_add_u32_e32 v0, 0xfffffe80, v6
	s_mov_b32 s2, 0xaaaaaaab
	v_mul_hi_u32 v0, v0, s2
	v_lshrrev_b32_e32 v0, 8, v0
	s_andn2_saveexec_b64 s[26:27], s[26:27]
	s_mov_b32 s2, 0x2aaaaaab
	v_mul_hi_i32 v0, v27, s2
	v_lshrrev_b32_e32 v3, 31, v0
	v_ashrrev_i32_e32 v0, 3, v0
	v_add_u32_e32 v0, v0, v3
	s_or_b64 exec, exec, s[26:27]
	v_cmp_eq_u32_e64 s[42:43], 0, v0
	s_nop 1
	v_cndmask_b32_e64 v0, v239, 0, s[42:43]
	v_cmp_ne_u32_sdwa s[26:27], v2, v0 src0_sel:BYTE_0 src1_sel:DWORD
	v_cndmask_b32_e64 v3, 1, -1, s[42:43]
